# transposer: tensor order rotated per workgroup so pipeline drains at tensor switches do not coincide chip-wide
# baseline (speedup 1.0000x reference)
; #define LAS __attribute__((address_space(3)))
; __device__ __forceinline__ void transpose_tensor(const float* W, const float* g, int gstep, int nl, int K, int N, bf16* WT, LAS float* scr, int gw, int NGW, int lane) {
;     const int nblk = N / 32, per = (K / 64) * nblk, total = nl * per;
;     for (int it = gw; it < total; it += NGW) { const int l = it / per, r = it - l * per;
;         transpose_item(W + (size_t)l * K * N, g ? g + (size_t)l * gstep : nullptr, K, N, WT + (size_t)l * K * N, scr, r / nblk, r % nblk, lane); }
; __global__ void __launch_bounds__(NWAVES * 64, 2) fwd(Args args) {
;     ...
;         transpose_tensor(ka->in[8], ka->in[4], 2 * DM, 2, DM, NQKV, WSB(WS_WQKVA), scr, gw, NGW, lane);
;         transpose_tensor(ka->in[13], ka->in[4] + DM, 2 * DM, 2, DM, 3 * NQKV, WSB(WS_WQKVB), scr, gw, NGW, lane);
;         transpose_tensor(ka->in[12], nullptr, 0, 2, DM, DM, WSB(WS_WOA), scr, gw, NGW, lane);
;         transpose_tensor(ka->in[17], nullptr, 0, 2, DM, DM, WSB(WS_WOB), scr, gw, NGW, lane);
;         transpose_tensor(ka->in[18], ka->in[5], DM, 4, DM, XHEAD * HD, WSB(WS_WQX), scr, gw, NGW, lane);
;         transpose_tensor(ka->in[19], nullptr, 0, 4, DM, 2 * XHEAD * HD, WSB(WS_WKVX), scr, gw, NGW, lane);
;         transpose_tensor(ka->in[22], nullptr, 0, 4, XHEAD * HD, DM, WSB(WS_WOX), scr, gw, NGW, lane);
;         transpose_tensor(ka->in[23], ka->in[7], DM, 4, DM, DFF, WSB(WS_WUP), scr, gw, NGW, lane);
;         transpose_tensor(ka->in[24], nullptr, 0, 4, DFF, DM, WSB(WS_WDN), scr, gw, NGW, lane);
.LBB0_13:
.LBB0_14:
	v_readlane_b32 s10, v252, 0
	v_readlane_b32 s11, v252, 1
	v_lshrrev_b32_e32 v100, 6, v0
	v_and_b32_e32 v101, 63, v0
	s_load_dwordx2 s[12:13], s[10:11], 0xd0
	v_readfirstlane_b32 s14, v100
	v_lshrrev_b32_e32 v102, 5, v101
	v_and_b32_e32 v103, 31, v101
	v_and_b32_e32 v105, 7, v101
	v_lshrrev_b32_e32 v106, 3, v101
	s_lshl_b32 s15, s59, 3
	s_add_i32 s15, s15, s14
	s_lshl_b32 s16, s60, 3
	s_lshl_b32 s17, s14, 14
	v_mad_u32_u24 v104, v102, 33, v103
	v_lshl_add_u32 v104, v104, 2, s17
	v_mul_u32_u24_e32 v107, 0x108, v105
	v_add_u32_e32 v107, v107, v106
	v_lshl_add_u32 v107, v107, 2, s17
	v_lshlrev_b32_e32 v108, 5, v105
	v_lshlrev_b32_e32 v109, 2, v103
	v_lshlrev_b32_e32 v105, 4, v105
	s_mul_hi_u32 s61, s59, 0x1c71c71d
	s_mul_i32 s61, s61, 9
	s_sub_u32 s18, s59, s61
	s_mov_b32 s65, 0
	s_waitcnt lgkmcnt(0)

; #define LAS __attribute__((address_space(3)))
; __device__ __forceinline__ void transpose_tensor(const float* W, const float* g, int gstep, int nl, int K, int N, bf16* WT, LAS float* scr, int gw, int NGW, int lane) {
;     const int nblk = N / 32, per = (K / 64) * nblk, total = nl * per;
;     for (int it = gw; it < total; it += NGW) { const int l = it / per, r = it - l * per;
;         transpose_item(W + (size_t)l * K * N, g ? g + (size_t)l * gstep : nullptr, K, N, WT + (size_t)l * K * N, scr, r / nblk, r % nblk, lane); }
.Lwt_next:
	s_add_u32 s65, s65, 1
	s_cmp_ge_u32 s65, 9
	s_cbranch_scc1 .Lwt_end
	s_add_u32 s18, s18, 1
	s_cmp_eq_u32 s18, 9
	s_cselect_b32 s18, 0, s18
	s_branch .Lwt_dispatch
